# P2 light pass: CQ/CKV loads hoisted next to the U window loads; P0 norm pass: gain vector loaded once outside the row loop
# speedup vs baseline: 1.0040x; 1.0040x over previous
.LBB0_156:
	s_cmpk_gt_i32 s88, 0x7fff
	s_cbranch_scc1 .LBB0_159
	v_mbcnt_lo_u32_b32 v1, -1, 0
	v_mbcnt_hi_u32_b32 v1, -1, v1
	v_and_b32_e32 v6, 64, v1
	v_readlane_b32 s4, v254, 7
	s_waitcnt vmcnt(23)
	v_add_u32_e32 v12, 64, v6
	v_xor_b32_e32 v6, 1, v1
	v_readlane_b32 s5, v254, 8
	v_cmp_lt_i32_e32 vcc, v6, v12
	v_xor_b32_e32 v7, 2, v1
	s_load_dwordx2 s[0:1], s[4:5], 0x18
	s_load_dwordx2 s[2:3], s[4:5], 0x0
	v_cndmask_b32_e32 v6, v1, v6, vcc
	v_cmp_lt_i32_e32 vcc, v7, v12
	v_xor_b32_e32 v9, 4, v1
	v_xor_b32_e32 v10, 8, v1
	v_cndmask_b32_e32 v7, v1, v7, vcc
	v_cmp_lt_i32_e32 vcc, v9, v12
	v_xor_b32_e32 v11, 16, v1
	s_waitcnt vmcnt(10)
	v_lshlrev_b64 v[4:5], 4, v[40:41]
	v_cndmask_b32_e32 v9, v1, v9, vcc
	v_cmp_lt_i32_e32 vcc, v10, v12
	v_xor_b32_e32 v13, 32, v1
	s_ashr_i32 s89, s88, 31
	v_cndmask_b32_e32 v10, v1, v10, vcc
	v_cmp_lt_i32_e32 vcc, v11, v12
	s_waitcnt lgkmcnt(0)
	v_lshl_add_u64 v[2:3], s[0:1], 0, v[4:5]
	s_lshl_b64 s[0:1], s[88:89], 11
	v_cndmask_b32_e32 v11, v1, v11, vcc
	v_cmp_lt_i32_e32 vcc, v13, v12
	s_add_u32 s0, s8, s0
	s_addc_u32 s1, s9, s1
	v_cndmask_b32_e32 v1, v1, v13, vcc
	v_lshlrev_b32_e32 v12, 2, v1
	v_ashrrev_i32_e32 v1, 31, v0
	v_lshl_add_u64 v[0:1], v[0:1], 1, s[0:1]
	s_mov_b64 s[0:1], 0x5000000
	s_ashr_i32 s73, s72, 31
	v_lshl_add_u64 v[0:1], v[0:1], 0, s[0:1]
	s_lshl_b64 s[0:1], s[72:73], 11
	s_lshl_b64 s[4:5], s[88:89], 12
	s_add_u32 s2, s2, s4
	s_addc_u32 s3, s3, s5
	v_lshl_add_u64 v[4:5], s[2:3], 0, v[4:5]
	s_mov_b64 s[2:3], 0xc00
	v_lshlrev_b32_e32 v6, 2, v6
	v_lshlrev_b32_e32 v7, 2, v7
	v_lshlrev_b32_e32 v9, 2, v9
	v_lshlrev_b32_e32 v10, 2, v10
	v_lshlrev_b32_e32 v11, 2, v11
	v_lshl_add_u64 v[4:5], v[4:5], 0, s[2:3]
	s_lshl_b64 s[2:3], s[72:73], 12
	v_mov_b32_e32 v13, 0x358637bd
	s_mov_b32 s4, 0x800000
	s_mov_b32 s5, s88
	global_load_dwordx4 v[52:55], v[2:3], off
	global_load_dwordx4 v[56:59], v[2:3], off offset:1024
	global_load_dwordx4 v[60:63], v[2:3], off offset:2048
	global_load_dwordx4 v[64:67], v[2:3], off offset:3072
	s_waitcnt vmcnt(0)
.LBB0_158:
	global_load_dwordx4 v[14:17], v[4:5], off offset:-3072
	global_load_dwordx4 v[18:21], v[4:5], off offset:-2048
	global_load_dwordx4 v[22:25], v[4:5], off offset:-1024
	global_load_dwordx4 v[26:29], v[4:5], off
	s_add_i32 s5, s5, s72
	v_lshl_add_u64 v[4:5], v[4:5], 0, s[2:3]
	s_cmp_lt_i32 s5, 0x8000
	s_waitcnt vmcnt(3)
	v_pk_mul_f32 v[34:35], v[16:17], v[16:17]
	v_pk_mul_f32 v[36:37], v[14:15], v[14:15]
	s_waitcnt vmcnt(2)
	v_pk_mul_f32 v[38:39], v[20:21], v[20:21]
	v_pk_mul_f32 v[40:41], v[18:19], v[18:19]
	v_pk_mov_b32 v[46:47], v[36:37], v[34:35] op_sel:[1,0]
	v_mov_b32_e32 v37, v35
	v_pk_mov_b32 v[34:35], v[40:41], v[38:39] op_sel:[1,0]
	v_mov_b32_e32 v41, v39
	s_waitcnt vmcnt(0)
	v_mul_f32_e32 v45, v26, v26
	v_mul_f32_e32 v42, v23, v23
	v_mul_f32_e32 v44, v25, v25
	v_pk_add_f32 v[36:37], v[46:47], v[36:37]
	v_pk_add_f32 v[34:35], v[34:35], v[40:41]
	v_mul_f32_e32 v48, v27, v27
	v_mul_f32_e32 v49, v28, v28
	v_mul_f32_e32 v50, v29, v29
	v_pk_fma_f32 v[38:39], v[22:23], v[22:23], v[42:43] op_sel_hi:[1,1,0]
	v_pk_fma_f32 v[42:43], v[24:25], v[24:25], v[44:45] op_sel_hi:[1,1,0]
	v_pk_add_f32 v[36:37], v[36:37], v[36:37] op_sel:[0,1] op_sel_hi:[1,0]
	v_pk_add_f32 v[34:35], v[34:35], v[34:35] op_sel:[0,1] op_sel_hi:[1,0]
	v_mov_b32_e32 v39, v49
	v_mov_b32_e32 v43, v50
	v_mov_b32_e32 v37, v45
	v_mov_b32_e32 v35, v48
	v_pk_add_f32 v[38:39], v[38:39], v[42:43]
	v_pk_add_f32 v[34:35], v[36:37], v[34:35]
	s_nop 0
	v_pk_add_f32 v[34:35], v[34:35], v[38:39]
	s_nop 0
	v_add_f32_e32 v34, v34, v35
	ds_bpermute_b32 v35, v6, v34
	s_waitcnt lgkmcnt(0)
	v_add_f32_e32 v34, v34, v35
	ds_bpermute_b32 v35, v7, v34
	s_waitcnt lgkmcnt(0)
	v_add_f32_e32 v34, v34, v35
	ds_bpermute_b32 v35, v9, v34
	s_waitcnt lgkmcnt(0)
	v_add_f32_e32 v34, v34, v35
	ds_bpermute_b32 v35, v10, v34
	s_waitcnt lgkmcnt(0)
	v_add_f32_e32 v34, v34, v35
	ds_bpermute_b32 v35, v11, v34
	s_waitcnt lgkmcnt(0)
	v_add_f32_e32 v34, v34, v35
	ds_bpermute_b32 v35, v12, v34
	s_waitcnt lgkmcnt(0)
	v_add_f32_e32 v34, v34, v35
	v_fmamk_f32 v34, v34, 0x3a800000, v13
	v_mul_f32_e32 v35, 0x4b800000, v34
	v_cmp_gt_f32_e32 vcc, s4, v34
	s_nop 1
	v_cndmask_b32_e32 v34, v34, v35, vcc
	v_rsq_f32_e32 v34, v34
	s_nop 0
	v_mul_f32_e32 v35, 0x45800000, v34
	v_cndmask_b32_e32 v34, v34, v35, vcc
	v_pk_mul_f32 v[14:15], v[14:15], v[34:35] op_sel_hi:[1,0]
	v_pk_mul_f32 v[16:17], v[16:17], v[34:35] op_sel_hi:[1,0]
	v_pk_mul_f32 v[14:15], v[52:53], v[14:15]
	v_pk_mul_f32 v[16:17], v[54:55], v[16:17]
	v_cvt_pk_bf16_f32 v14, v14, v15
	v_cvt_pk_bf16_f32 v15, v16, v17
	global_store_dwordx2 v[0:1], v[14:15], off
	v_pk_mul_f32 v[18:19], v[18:19], v[34:35] op_sel_hi:[1,0]
	v_pk_mul_f32 v[20:21], v[20:21], v[34:35] op_sel_hi:[1,0]
	v_pk_mul_f32 v[14:15], v[56:57], v[18:19]
	v_pk_mul_f32 v[16:17], v[58:59], v[20:21]
	v_cvt_pk_bf16_f32 v14, v14, v15
	v_cvt_pk_bf16_f32 v15, v16, v17
	global_store_dwordx2 v[0:1], v[14:15], off offset:512
	v_pk_mul_f32 v[18:19], v[22:23], v[34:35] op_sel_hi:[1,0]
	v_pk_mul_f32 v[20:21], v[24:25], v[34:35] op_sel_hi:[1,0]
	v_pk_mul_f32 v[14:15], v[60:61], v[18:19]
	v_pk_mul_f32 v[16:17], v[62:63], v[20:21]
	v_cvt_pk_bf16_f32 v14, v14, v15
	v_cvt_pk_bf16_f32 v15, v16, v17
	global_store_dwordx2 v[0:1], v[14:15], off offset:1024
	v_pk_mul_f32 v[18:19], v[26:27], v[34:35] op_sel_hi:[1,0]
	v_pk_mul_f32 v[20:21], v[28:29], v[34:35] op_sel_hi:[1,0]
	v_pk_mul_f32 v[14:15], v[64:65], v[18:19]
	v_pk_mul_f32 v[16:17], v[66:67], v[20:21]
	v_cvt_pk_bf16_f32 v14, v14, v15
	v_cvt_pk_bf16_f32 v15, v16, v17
	global_store_dwordx2 v[0:1], v[14:15], off offset:1536
	v_lshl_add_u64 v[0:1], v[0:1], 0, s[0:1]
	s_cbranch_scc1 .LBB0_158

.LBB0_374:
	s_or_b64 exec, exec, s[2:3]
	s_waitcnt vmcnt(0)
	v_lshlrev_b32_e32 v94, 16, v24
	v_and_b32_e32 v95, 0xffff0000, v24
	v_lshlrev_b32_e32 v82, 16, v25
	v_and_b32_e32 v83, 0xffff0000, v25
	v_lshlrev_b32_e32 v80, 16, v26
	v_and_b32_e32 v81, 0xffff0000, v26
	v_lshlrev_b32_e32 v24, 16, v27
	v_and_b32_e32 v25, 0xffff0000, v27
	v_lshlrev_b32_e32 v26, 16, v8
	v_and_b32_e32 v27, 0xffff0000, v8
	v_lshlrev_b32_e32 v8, 16, v9
	v_and_b32_e32 v9, 0xffff0000, v9
	v_lshlrev_b32_e32 v96, 16, v4
	v_and_b32_e32 v97, 0xffff0000, v4
	v_pk_add_f32 v[8:9], v[82:83], v[8:9]
	v_lshlrev_b32_e32 v4, 16, v5
	v_and_b32_e32 v5, 0xffff0000, v5
	v_pk_add_f32 v[4:5], v[8:9], v[4:5]
	v_lshlrev_b32_e32 v8, 16, v21
	v_and_b32_e32 v9, 0xffff0000, v21
	v_pk_add_f32 v[4:5], v[4:5], v[8:9]
	v_lshlrev_b32_e32 v8, 16, v13
	v_and_b32_e32 v9, 0xffff0000, v13
	v_pk_add_f32 v[4:5], v[4:5], v[8:9]
	v_lshlrev_b32_e32 v8, 16, v37
	v_and_b32_e32 v9, 0xffff0000, v37
	v_pk_add_f32 v[26:27], v[94:95], v[26:27]
	v_pk_add_f32 v[4:5], v[4:5], v[8:9]
	v_lshlrev_b32_e32 v8, 16, v29
	v_and_b32_e32 v9, 0xffff0000, v29
	v_pk_add_f32 v[26:27], v[26:27], v[96:97]
	v_lshlrev_b32_e32 v96, 16, v20
	v_and_b32_e32 v97, 0xffff0000, v20
	v_pk_add_f32 v[8:9], v[4:5], v[8:9]
	v_lshlrev_b32_e32 v4, 16, v10
	v_and_b32_e32 v5, 0xffff0000, v10
	v_pk_add_f32 v[26:27], v[26:27], v[96:97]
	v_lshlrev_b32_e32 v96, 16, v12
	v_and_b32_e32 v97, 0xffff0000, v12
	v_pk_add_f32 v[4:5], v[80:81], v[4:5]
	v_lshlrev_b32_e32 v12, 16, v6
	v_and_b32_e32 v13, 0xffff0000, v6
	v_pk_add_f32 v[4:5], v[4:5], v[12:13]
	v_lshlrev_b32_e32 v12, 16, v22
	v_and_b32_e32 v13, 0xffff0000, v22
	v_pk_add_f32 v[4:5], v[4:5], v[12:13]
	v_lshlrev_b32_e32 v12, 16, v14
	v_and_b32_e32 v13, 0xffff0000, v14
	v_pk_add_f32 v[4:5], v[4:5], v[12:13]
	v_lshlrev_b32_e32 v12, 16, v38
	v_and_b32_e32 v13, 0xffff0000, v38
	v_pk_add_f32 v[4:5], v[4:5], v[12:13]
	v_lshlrev_b32_e32 v12, 16, v30
	v_and_b32_e32 v13, 0xffff0000, v30
	v_pk_add_f32 v[12:13], v[4:5], v[12:13]
	v_lshlrev_b32_e32 v4, 16, v11
	v_and_b32_e32 v5, 0xffff0000, v11
	v_pk_add_f32 v[4:5], v[24:25], v[4:5]
	v_lshlrev_b32_e32 v6, 16, v7
	v_and_b32_e32 v7, 0xffff0000, v7
	v_pk_add_f32 v[4:5], v[4:5], v[6:7]
	v_lshlrev_b32_e32 v6, 16, v23
	v_and_b32_e32 v7, 0xffff0000, v23
	v_pk_add_f32 v[4:5], v[4:5], v[6:7]
	v_lshlrev_b32_e32 v6, 16, v15
	v_and_b32_e32 v7, 0xffff0000, v15
	v_lshlrev_b32_e32 v14, 16, v50
	v_and_b32_e32 v15, 0xffff0000, v50
	v_cvt_f32_i32_e32 v50, v92
	v_lshlrev_b32_e32 v20, 16, v51
	v_and_b32_e32 v21, 0xffff0000, v51
	v_pk_add_f32 v[26:27], v[26:27], v[96:97]
	v_div_scale_f32 v51, s[2:3], v50, v50, 1.0
	v_lshlrev_b32_e32 v96, 16, v36
	v_and_b32_e32 v97, 0xffff0000, v36
	v_pk_add_f32 v[4:5], v[4:5], v[6:7]
	v_lshlrev_b32_e32 v6, 16, v39
	v_and_b32_e32 v7, 0xffff0000, v39
	v_lshlrev_b32_e32 v38, 16, v60
	v_and_b32_e32 v39, 0xffff0000, v60
	v_rcp_f32_e32 v60, v51
	v_pk_add_f32 v[26:27], v[26:27], v[96:97]
	v_lshlrev_b32_e32 v96, 16, v28
	v_and_b32_e32 v97, 0xffff0000, v28
	v_pk_add_f32 v[4:5], v[4:5], v[6:7]
	v_lshlrev_b32_e32 v6, 16, v31
	v_and_b32_e32 v7, 0xffff0000, v31
	v_pk_add_f32 v[26:27], v[26:27], v[96:97]
	v_pk_add_f32 v[10:11], v[4:5], v[6:7]
	v_lshlrev_b32_e32 v4, 16, v48
	v_and_b32_e32 v5, 0xffff0000, v48
	v_lshlrev_b32_e32 v6, 16, v49
	v_and_b32_e32 v7, 0xffff0000, v49
	v_lshlrev_b32_e32 v22, 16, v44
	v_and_b32_e32 v23, 0xffff0000, v44
	v_lshlrev_b32_e32 v28, 16, v45
	v_and_b32_e32 v29, 0xffff0000, v45
	v_pk_add_f32 v[4:5], v[26:27], v[4:5]
	v_pk_add_f32 v[6:7], v[8:9], v[6:7]
	v_lshlrev_b32_e32 v44, 16, v61
	v_and_b32_e32 v45, 0xffff0000, v61
	v_fma_f32 v61, -v51, v60, 1.0
	v_pk_add_f32 v[4:5], v[4:5], v[22:23]
	v_pk_add_f32 v[6:7], v[6:7], v[28:29]
	v_fmac_f32_e32 v60, v61, v60
	v_div_scale_f32 v61, vcc, 1.0, v50, 1.0
	v_pk_add_f32 v[4:5], v[4:5], v[38:39]
	v_lshlrev_b32_e32 v22, 16, v16
	v_and_b32_e32 v23, 0xffff0000, v16
	v_pk_add_f32 v[6:7], v[6:7], v[44:45]
	v_lshlrev_b32_e32 v8, 16, v17
	v_and_b32_e32 v9, 0xffff0000, v17
	v_lshlrev_b32_e32 v30, 16, v46
	v_and_b32_e32 v31, 0xffff0000, v46
	v_lshlrev_b32_e32 v36, 16, v47
	v_and_b32_e32 v37, 0xffff0000, v47
	v_lshlrev_b32_e32 v46, 16, v62
	v_and_b32_e32 v47, 0xffff0000, v62
	v_mul_f32_e32 v62, v61, v60
	v_pk_add_f32 v[4:5], v[4:5], v[22:23]
	v_lshlrev_b32_e32 v22, 16, v40
	v_and_b32_e32 v23, 0xffff0000, v40
	v_pk_add_f32 v[6:7], v[6:7], v[8:9]
	v_lshlrev_b32_e32 v8, 16, v41
	v_and_b32_e32 v9, 0xffff0000, v41
	v_lshlrev_b32_e32 v48, 16, v63
	v_and_b32_e32 v49, 0xffff0000, v63
	v_fma_f32 v63, -v51, v62, v61
	v_pk_add_f32 v[4:5], v[4:5], v[22:23]
	v_lshlrev_b32_e32 v22, 16, v32
	v_and_b32_e32 v23, 0xffff0000, v32
	v_pk_add_f32 v[6:7], v[6:7], v[8:9]
	v_lshlrev_b32_e32 v8, 16, v33
	v_and_b32_e32 v9, 0xffff0000, v33
	v_fmac_f32_e32 v62, v63, v60
	v_pk_add_f32 v[4:5], v[4:5], v[22:23]
	v_lshlrev_b32_e32 v22, 16, v56
	v_and_b32_e32 v23, 0xffff0000, v56
	v_pk_add_f32 v[6:7], v[6:7], v[8:9]
	v_lshlrev_b32_e32 v8, 16, v57
	v_and_b32_e32 v9, 0xffff0000, v57
	v_fma_f32 v51, -v51, v62, v61
	v_pk_add_f32 v[4:5], v[4:5], v[22:23]
	v_lshlrev_b32_e32 v22, 16, v52
	v_and_b32_e32 v23, 0xffff0000, v52
	v_pk_add_f32 v[6:7], v[6:7], v[8:9]
	v_lshlrev_b32_e32 v8, 16, v53
	v_and_b32_e32 v9, 0xffff0000, v53
	v_div_fmas_f32 v51, v51, v60, v62
	v_pk_add_f32 v[4:5], v[4:5], v[22:23]
	v_lshlrev_b32_e32 v22, 16, v64
	v_and_b32_e32 v23, 0xffff0000, v64
	v_pk_add_f32 v[6:7], v[6:7], v[8:9]
	v_lshlrev_b32_e32 v8, 16, v65
	v_and_b32_e32 v9, 0xffff0000, v65
	v_div_fixup_f32 v50, v51, v50, 1.0
	v_pk_add_f32 v[4:5], v[4:5], v[22:23]
	v_pk_add_f32 v[6:7], v[6:7], v[8:9]
	v_pk_fma_f32 v[4:5], v[50:51], v[4:5], v[94:95] op_sel_hi:[0,1,1] neg_lo:[0,0,1] neg_hi:[0,0,1]
	v_pk_fma_f32 v[6:7], v[50:51], v[6:7], v[82:83] op_sel_hi:[0,1,1] neg_lo:[0,0,1] neg_hi:[0,0,1]
	v_cvt_pk_bf16_f32 v4, v4, v5
	v_cvt_pk_bf16_f32 v5, v6, v7
	v_pk_add_f32 v[6:7], v[12:13], v[14:15]
	v_lshlrev_b32_e32 v8, 16, v18
	v_pk_add_f32 v[6:7], v[6:7], v[30:31]
	v_and_b32_e32 v9, 0xffff0000, v18
	v_pk_add_f32 v[6:7], v[6:7], v[46:47]
	s_add_i32 s6, s6, s4
	v_pk_add_f32 v[6:7], v[6:7], v[8:9]
	v_lshlrev_b32_e32 v8, 16, v42
	v_and_b32_e32 v9, 0xffff0000, v42
	v_pk_add_f32 v[6:7], v[6:7], v[8:9]
	v_lshlrev_b32_e32 v8, 16, v34
	v_and_b32_e32 v9, 0xffff0000, v34
	v_pk_add_f32 v[6:7], v[6:7], v[8:9]
	v_lshlrev_b32_e32 v8, 16, v58
	v_and_b32_e32 v9, 0xffff0000, v58
	v_pk_add_f32 v[6:7], v[6:7], v[8:9]
	v_lshlrev_b32_e32 v8, 16, v54
	v_and_b32_e32 v9, 0xffff0000, v54
	v_pk_add_f32 v[6:7], v[6:7], v[8:9]
	v_lshlrev_b32_e32 v8, 16, v66
	v_and_b32_e32 v9, 0xffff0000, v66
	v_pk_add_f32 v[6:7], v[6:7], v[8:9]
	v_pk_add_f32 v[8:9], v[10:11], v[20:21]
	v_lshlrev_b32_e32 v10, 16, v19
	v_pk_add_f32 v[8:9], v[8:9], v[36:37]
	v_and_b32_e32 v11, 0xffff0000, v19
	v_pk_add_f32 v[8:9], v[8:9], v[48:49]
	v_pk_fma_f32 v[6:7], v[50:51], v[6:7], v[80:81] op_sel_hi:[0,1,1] neg_lo:[0,0,1] neg_hi:[0,0,1]
	v_pk_add_f32 v[8:9], v[8:9], v[10:11]
	v_lshlrev_b32_e32 v10, 16, v43
	v_and_b32_e32 v11, 0xffff0000, v43
	v_pk_add_f32 v[8:9], v[8:9], v[10:11]
	v_lshlrev_b32_e32 v10, 16, v35
	v_and_b32_e32 v11, 0xffff0000, v35
	v_pk_add_f32 v[8:9], v[8:9], v[10:11]
	v_lshlrev_b32_e32 v10, 16, v59
	v_and_b32_e32 v11, 0xffff0000, v59
	v_pk_add_f32 v[8:9], v[8:9], v[10:11]
	v_lshlrev_b32_e32 v10, 16, v55
	v_and_b32_e32 v11, 0xffff0000, v55
	v_pk_add_f32 v[8:9], v[8:9], v[10:11]
	v_lshlrev_b32_e32 v10, 16, v67
	v_and_b32_e32 v11, 0xffff0000, v67
	v_pk_add_f32 v[8:9], v[8:9], v[10:11]
	v_cvt_pk_bf16_f32 v6, v6, v7
	v_pk_fma_f32 v[8:9], v[50:51], v[8:9], v[24:25] op_sel_hi:[0,1,1] neg_lo:[0,0,1] neg_hi:[0,0,1]
	v_cvt_pk_bf16_f32 v7, v8, v9
	v_add_co_u32_e32 v8, vcc, s5, v78
	s_add_i32 s2, s6, 15
	s_nop 0
	v_addc_co_u32_e32 v9, vcc, 0, v79, vcc
	global_store_dwordx4 v[8:9], v[4:7], off
	s_cmp_lt_i32 s2, 0x8000
	v_lshl_add_u64 v[76:77], v[76:77], 0, s[14:15]
	v_lshl_add_u64 v[4:5], s[0:1], 0, v[74:75]
	v_add_co_u32_e32 v6, vcc, s16, v4
	v_lshl_add_u64 v[74:75], v[74:75], 0, s[12:13]
	s_nop 0
	v_addc_co_u32_e32 v7, vcc, 0, v5, vcc
	v_mov_b32_e32 v6, v102
	v_mov_b32_e32 v7, v103
	v_and_b32_e32 v9, 0xffff0000, v7
	v_and_b32_e32 v11, 0xffff0000, v6
	v_lshlrev_b32_e32 v8, 16, v7
	v_lshlrev_b32_e32 v10, 16, v6
	v_mov_b32_e32 v12, v11
	v_mov_b32_e32 v13, v9
	v_mov_b32_e32 v6, v10
	v_mov_b32_e32 v7, v8
	v_pk_mul_f32 v[12:13], v[12:13], v[12:13]
	s_nop 0
	v_pk_fma_f32 v[6:7], v[6:7], v[6:7], v[12:13]
	s_nop 0
	v_add_f32_e32 v6, v6, v7
	ds_bpermute_b32 v7, v85, v6
	s_waitcnt lgkmcnt(0)
	v_add_f32_e32 v6, v6, v7
	ds_bpermute_b32 v7, v86, v6
	s_waitcnt lgkmcnt(0)
	v_add_f32_e32 v6, v6, v7
	ds_bpermute_b32 v7, v87, v6
	s_waitcnt lgkmcnt(0)
	v_add_f32_e32 v6, v6, v7
	ds_bpermute_b32 v7, v88, v6
	s_waitcnt lgkmcnt(0)
	v_add_f32_e32 v6, v6, v7
	ds_bpermute_b32 v7, v89, v6
	s_waitcnt lgkmcnt(0)
	v_add_f32_e32 v6, v6, v7
	ds_bpermute_b32 v7, v90, v6
	s_waitcnt lgkmcnt(0)
	v_add_f32_e32 v6, v6, v7
	v_fmamk_f32 v6, v6, 0x3b800000, v91
	v_mul_f32_e32 v7, 0x4b800000, v6
	v_cmp_gt_f32_e32 vcc, s17, v6
	s_nop 1
	v_cndmask_b32_e32 v6, v6, v7, vcc
	v_rsq_f32_e32 v6, v6
	s_nop 0
	v_mul_f32_e32 v7, 0x45800000, v6
	v_cndmask_b32_e32 v6, v6, v7, vcc
	v_pk_mul_f32 v[10:11], v[6:7], v[10:11] op_sel_hi:[0,1]
	v_pk_mul_f32 v[6:7], v[6:7], v[8:9] op_sel_hi:[0,1]
	v_pk_mul_f32 v[10:11], v[0:1], v[10:11]
	v_pk_mul_f32 v[6:7], v[2:3], v[6:7]
	v_add_co_u32_e32 v4, vcc, s18, v4
	v_cvt_pk_bf16_f32 v10, v10, v11
	v_cvt_pk_bf16_f32 v11, v6, v7
	v_addc_co_u32_e32 v5, vcc, 0, v5, vcc
	global_store_dwordx2 v[4:5], v[10:11], off
	v_lshl_add_u64 v[4:5], s[0:1], 0, v[72:73]
	v_add_co_u32_e32 v6, vcc, s19, v4
	v_lshl_add_u64 v[72:73], v[72:73], 0, s[8:9]
	s_nop 0
	v_addc_co_u32_e32 v7, vcc, 0, v5, vcc
	v_mov_b32_e32 v7, v104
	v_lshlrev_b32_e32 v6, 16, v7
	v_and_b32_e32 v7, 0xffff0000, v7
	v_pk_mul_f32 v[8:9], v[6:7], v[6:7]
	s_nop 0
	v_add_f32_e32 v8, v8, v9
	ds_bpermute_b32 v9, v85, v8
	s_waitcnt lgkmcnt(0)
	v_add_f32_e32 v8, v8, v9
	ds_bpermute_b32 v9, v86, v8
	s_waitcnt lgkmcnt(0)
	v_add_f32_e32 v8, v8, v9
	ds_bpermute_b32 v9, v87, v8
	s_waitcnt lgkmcnt(0)
	v_add_f32_e32 v8, v8, v9
	ds_bpermute_b32 v9, v88, v8
	s_waitcnt lgkmcnt(0)
	v_add_f32_e32 v8, v8, v9
	ds_bpermute_b32 v9, v89, v8
	s_waitcnt lgkmcnt(0)
	v_add_f32_e32 v8, v8, v9
	ds_bpermute_b32 v9, v90, v8
	s_waitcnt lgkmcnt(0)
	v_add_f32_e32 v8, v8, v9
	v_fmamk_f32 v8, v8, 0x3c000000, v91
	v_mul_f32_e32 v9, 0x4b800000, v8
	v_cmp_gt_f32_e32 vcc, s17, v8
	s_nop 1
	v_cndmask_b32_e32 v8, v8, v9, vcc
	v_rsq_f32_e32 v8, v8
	s_nop 0
	v_mul_f32_e32 v9, 0x45800000, v8
	v_cndmask_b32_e32 v8, v8, v9, vcc
	v_pk_mul_f32 v[6:7], v[8:9], v[6:7] op_sel_hi:[0,1]
	v_pk_mul_f32 v[6:7], v[68:69], v[6:7]
	v_add_co_u32_e32 v4, vcc, 0x13a00000, v4
	v_cvt_pk_bf16_f32 v6, v6, v7
	s_nop 0
	v_addc_co_u32_e32 v5, vcc, 0, v5, vcc
	global_store_dword v[4:5], v6, off
	s_cbranch_scc0 .LBB0_405
.LBB0_375:
	v_lshl_add_u64 v[100:101], s[0:1], 0, v[74:75]
	v_add_co_u32_e32 v100, vcc, s16, v100
	s_nop 1
	v_addc_co_u32_e32 v101, vcc, 0, v101, vcc
	global_load_dwordx2 v[102:103], v[100:101], off
	v_lshl_add_u64 v[100:101], s[0:1], 0, v[72:73]
	v_add_co_u32_e32 v100, vcc, s19, v100
	s_nop 1
	v_addc_co_u32_e32 v101, vcc, 0, v101, vcc
	global_load_dword v104, v[100:101], off
	v_lshl_add_u64 v[78:79], s[0:1], 0, v[76:77]
	v_add_co_u32_e32 v4, vcc, 0xd000000, v78
	s_add_i32 s2, s6, 15
	s_nop 0
	v_addc_co_u32_e32 v5, vcc, 0, v79, vcc
	global_load_dwordx4 v[24:27], v[4:5], off
	s_and_b32 s2, s2, 0x3fff
	s_add_i32 s2, s2, 1
	v_min_i32_e32 v92, s2, v84
	v_cmp_lt_i32_e32 vcc, 1, v92
	v_mov_b32_e32 v4, 0
	v_mov_b32_e32 v8, 0
	v_mov_b32_e32 v9, 0
	v_mov_b32_e32 v10, 0
	v_mov_b32_e32 v11, 0
	s_and_saveexec_b64 s[2:3], vcc
	s_cbranch_execz .LBB0_377
	s_add_i32 s22, s6, 14
	s_ashr_i32 s23, s22, 31
	s_lshl_b64 s[22:23], s[22:23], 10
	v_lshl_add_u64 v[6:7], v[70:71], 0, s[22:23]
	global_load_dwordx4 v[8:11], v[6:7], off
